# attention window mask dispatched per tile: only the q-tile the window edge crosses is compared, the other is untouched or filled with -inf
# speedup vs baseline: 1.0089x; 1.0024x over previous
.Latt_domask0:
	v_add_u32_e32 v164, s13, v183
	v_sub_u32_e32 v165, v162, v164
	s_bitcmp1_b32 s13, 5
	s_cbranch_scc1 .Latt_m0b
	v_cmp_lt_i32_e64 s[20:21], 0, v165
	v_cmp_lt_i32_e64 s[22:23], 1, v165
	v_cmp_lt_i32_e64 s[24:25], 2, v165
	v_cndmask_b32_e64 v80, v80, v205, s[20:21]
	v_cmp_lt_i32_e64 s[20:21], 3, v165
	v_cndmask_b32_e64 v81, v81, v205, s[22:23]
	v_cmp_lt_i32_e64 s[22:23], 8, v165
	v_cndmask_b32_e64 v82, v82, v205, s[24:25]
	v_cmp_lt_i32_e64 s[24:25], 9, v165
	v_cndmask_b32_e64 v83, v83, v205, s[20:21]
	v_cmp_lt_i32_e64 s[20:21], 10, v165
	v_cndmask_b32_e64 v84, v84, v205, s[22:23]
	v_cmp_lt_i32_e64 s[22:23], 11, v165
	v_cndmask_b32_e64 v85, v85, v205, s[24:25]
	v_cmp_lt_i32_e64 s[24:25], 16, v165
	v_cndmask_b32_e64 v86, v86, v205, s[20:21]
	v_cmp_lt_i32_e64 s[20:21], 17, v165
	v_cndmask_b32_e64 v87, v87, v205, s[22:23]
	v_cmp_lt_i32_e64 s[22:23], 18, v165
	v_cndmask_b32_e64 v88, v88, v205, s[24:25]
	v_cmp_lt_i32_e64 s[24:25], 19, v165
	v_cndmask_b32_e64 v89, v89, v205, s[20:21]
	v_cmp_lt_i32_e64 s[20:21], 24, v165
	v_cndmask_b32_e64 v90, v90, v205, s[22:23]
	v_cmp_lt_i32_e64 s[22:23], 25, v165
	v_cndmask_b32_e64 v91, v91, v205, s[24:25]
	v_cmp_lt_i32_e64 s[24:25], 26, v165
	v_cndmask_b32_e64 v92, v92, v205, s[20:21]
	v_cmp_lt_i32_e64 s[20:21], 27, v165
	v_cndmask_b32_e64 v93, v93, v205, s[22:23]
	v_cndmask_b32_e64 v94, v94, v205, s[24:25]
	v_cndmask_b32_e64 v95, v95, v205, s[20:21]
	v_mov_b32_e32 v64, v205
	v_mov_b32_e32 v65, v205
	v_mov_b32_e32 v66, v205
	v_mov_b32_e32 v67, v205
	v_mov_b32_e32 v68, v205
	v_mov_b32_e32 v69, v205
	v_mov_b32_e32 v70, v205
	v_mov_b32_e32 v71, v205
	v_mov_b32_e32 v72, v205
	v_mov_b32_e32 v73, v205
	v_mov_b32_e32 v74, v205
	v_mov_b32_e32 v75, v205
	v_mov_b32_e32 v76, v205
	v_mov_b32_e32 v77, v205
	v_mov_b32_e32 v78, v205
	v_mov_b32_e32 v79, v205
	s_branch .LBB0_822
.Latt_m0b:
	v_add_u32_e32 v166, 32, v165
	s_nop 0
	v_cmp_lt_i32_e64 s[20:21], 0, v166
	v_cmp_lt_i32_e64 s[22:23], 1, v166
	v_cmp_lt_i32_e64 s[24:25], 2, v166
	v_cndmask_b32_e64 v64, v64, v205, s[20:21]
	v_cmp_lt_i32_e64 s[20:21], 3, v166
	v_cndmask_b32_e64 v65, v65, v205, s[22:23]
	v_cmp_lt_i32_e64 s[22:23], 8, v166
	v_cndmask_b32_e64 v66, v66, v205, s[24:25]
	v_cmp_lt_i32_e64 s[24:25], 9, v166
	v_cndmask_b32_e64 v67, v67, v205, s[20:21]
	v_cmp_lt_i32_e64 s[20:21], 10, v166
	v_cndmask_b32_e64 v68, v68, v205, s[22:23]
	v_cmp_lt_i32_e64 s[22:23], 11, v166
	v_cndmask_b32_e64 v69, v69, v205, s[24:25]
	v_cmp_lt_i32_e64 s[24:25], 16, v166
	v_cndmask_b32_e64 v70, v70, v205, s[20:21]
	v_cmp_lt_i32_e64 s[20:21], 17, v166
	v_cndmask_b32_e64 v71, v71, v205, s[22:23]
	v_cmp_lt_i32_e64 s[22:23], 18, v166
	v_cndmask_b32_e64 v72, v72, v205, s[24:25]
	v_cmp_lt_i32_e64 s[24:25], 19, v166
	v_cndmask_b32_e64 v73, v73, v205, s[20:21]
	v_cmp_lt_i32_e64 s[20:21], 24, v166
	v_cndmask_b32_e64 v74, v74, v205, s[22:23]
	v_cmp_lt_i32_e64 s[22:23], 25, v166
	v_cndmask_b32_e64 v75, v75, v205, s[24:25]
	v_cmp_lt_i32_e64 s[24:25], 26, v166
	v_cndmask_b32_e64 v76, v76, v205, s[20:21]
	v_cmp_lt_i32_e64 s[20:21], 27, v166
	v_cndmask_b32_e64 v77, v77, v205, s[22:23]
	v_cndmask_b32_e64 v78, v78, v205, s[24:25]
	v_cndmask_b32_e64 v79, v79, v205, s[20:21]
	s_branch .LBB0_822

.Latt_domask2:
	v_add_u32_e32 v164, s13, v183
	v_sub_u32_e32 v165, v162, v164
	s_bitcmp1_b32 s13, 5
	s_cbranch_scc1 .Latt_m2b
	v_cmp_gt_i32_e64 s[20:21], 0, v165
	v_cmp_gt_i32_e64 s[22:23], 1, v165
	v_cmp_gt_i32_e64 s[24:25], 2, v165
	v_cndmask_b32_e64 v80, v80, v205, s[20:21]
	v_cmp_gt_i32_e64 s[20:21], 3, v165
	v_cndmask_b32_e64 v81, v81, v205, s[22:23]
	v_cmp_gt_i32_e64 s[22:23], 8, v165
	v_cndmask_b32_e64 v82, v82, v205, s[24:25]
	v_cmp_gt_i32_e64 s[24:25], 9, v165
	v_cndmask_b32_e64 v83, v83, v205, s[20:21]
	v_cmp_gt_i32_e64 s[20:21], 10, v165
	v_cndmask_b32_e64 v84, v84, v205, s[22:23]
	v_cmp_gt_i32_e64 s[22:23], 11, v165
	v_cndmask_b32_e64 v85, v85, v205, s[24:25]
	v_cmp_gt_i32_e64 s[24:25], 16, v165
	v_cndmask_b32_e64 v86, v86, v205, s[20:21]
	v_cmp_gt_i32_e64 s[20:21], 17, v165
	v_cndmask_b32_e64 v87, v87, v205, s[22:23]
	v_cmp_gt_i32_e64 s[22:23], 18, v165
	v_cndmask_b32_e64 v88, v88, v205, s[24:25]
	v_cmp_gt_i32_e64 s[24:25], 19, v165
	v_cndmask_b32_e64 v89, v89, v205, s[20:21]
	v_cmp_gt_i32_e64 s[20:21], 24, v165
	v_cndmask_b32_e64 v90, v90, v205, s[22:23]
	v_cmp_gt_i32_e64 s[22:23], 25, v165
	v_cndmask_b32_e64 v91, v91, v205, s[24:25]
	v_cmp_gt_i32_e64 s[24:25], 26, v165
	v_cndmask_b32_e64 v92, v92, v205, s[20:21]
	v_cmp_gt_i32_e64 s[20:21], 27, v165
	v_cndmask_b32_e64 v93, v93, v205, s[22:23]
	v_cndmask_b32_e64 v94, v94, v205, s[24:25]
	v_cndmask_b32_e64 v95, v95, v205, s[20:21]
	s_branch .LBB0_822
.Latt_m2b:
	v_add_u32_e32 v166, 32, v165
	v_mov_b32_e32 v80, v205
	v_mov_b32_e32 v81, v205
	v_mov_b32_e32 v82, v205
	v_mov_b32_e32 v83, v205
	v_mov_b32_e32 v84, v205
	v_mov_b32_e32 v85, v205
	v_mov_b32_e32 v86, v205
	v_mov_b32_e32 v87, v205
	v_mov_b32_e32 v88, v205
	v_mov_b32_e32 v89, v205
	v_mov_b32_e32 v90, v205
	v_mov_b32_e32 v91, v205
	v_mov_b32_e32 v92, v205
	v_mov_b32_e32 v93, v205
	v_mov_b32_e32 v94, v205
	v_mov_b32_e32 v95, v205
	v_cmp_gt_i32_e64 s[20:21], 0, v166
	v_cmp_gt_i32_e64 s[22:23], 1, v166
	v_cmp_gt_i32_e64 s[24:25], 2, v166
	v_cndmask_b32_e64 v64, v64, v205, s[20:21]
	v_cmp_gt_i32_e64 s[20:21], 3, v166
	v_cndmask_b32_e64 v65, v65, v205, s[22:23]
	v_cmp_gt_i32_e64 s[22:23], 8, v166
	v_cndmask_b32_e64 v66, v66, v205, s[24:25]
	v_cmp_gt_i32_e64 s[24:25], 9, v166
	v_cndmask_b32_e64 v67, v67, v205, s[20:21]
	v_cmp_gt_i32_e64 s[20:21], 10, v166
	v_cndmask_b32_e64 v68, v68, v205, s[22:23]
	v_cmp_gt_i32_e64 s[22:23], 11, v166
	v_cndmask_b32_e64 v69, v69, v205, s[24:25]
	v_cmp_gt_i32_e64 s[24:25], 16, v166
	v_cndmask_b32_e64 v70, v70, v205, s[20:21]
	v_cmp_gt_i32_e64 s[20:21], 17, v166
	v_cndmask_b32_e64 v71, v71, v205, s[22:23]
	v_cmp_gt_i32_e64 s[22:23], 18, v166
	v_cndmask_b32_e64 v72, v72, v205, s[24:25]
	v_cmp_gt_i32_e64 s[24:25], 19, v166
	v_cndmask_b32_e64 v73, v73, v205, s[20:21]
	v_cmp_gt_i32_e64 s[20:21], 24, v166
	v_cndmask_b32_e64 v74, v74, v205, s[22:23]
	v_cmp_gt_i32_e64 s[22:23], 25, v166
	v_cndmask_b32_e64 v75, v75, v205, s[24:25]
	v_cmp_gt_i32_e64 s[24:25], 26, v166
	v_cndmask_b32_e64 v76, v76, v205, s[20:21]
	v_cmp_gt_i32_e64 s[20:21], 27, v166
	v_cndmask_b32_e64 v77, v77, v205, s[22:23]
	v_cndmask_b32_e64 v78, v78, v205, s[24:25]
	v_cndmask_b32_e64 v79, v79, v205, s[20:21]
